# resid epilogue loads hoisted + memattn V row-major with tr reads and pipelined staging
# speedup vs baseline: 1.0166x; 1.0166x over previous
.LBB0_167:
	s_and_b64 vcc, exec, s[96:97]
	s_cbranch_vccz .LBB0_190
	s_cmp_eq_u32 s41, 1
	s_mov_b64 s[94:95], -1
	s_cbranch_scc0 .LBB0_190
	s_cmp_gt_i32 s18, -1
	s_cbranch_scc1 .LBB0_187
	v_lshlrev_b32_e32 v136, 1, v146
	s_lshl_b32 s82, s47, 9
	v_lshl_add_u32 v153, v152, 11, v136
	v_add_u32_e32 v153, s82, v153
	global_load_dwordx4 v[154:157], v153, s[28:29]
	global_load_dwordx4 v[180:183], v153, s[28:29] offset:256
	v_add_u32_e32 v159, 0x8000, v153
	global_load_dwordx4 v[184:187], v159, s[28:29]
	global_load_dwordx4 v[188:191], v159, s[28:29] offset:256
	v_add_u32_e32 v158, 0x10000, v153
	global_load_dwordx4 v[192:195], v158, s[28:29]
	global_load_dwordx4 v[196:199], v158, s[28:29] offset:256
	v_add_u32_e32 v159, 0x18000, v153
	global_load_dwordx4 v[200:203], v159, s[28:29]
	global_load_dwordx4 v[204:207], v159, s[28:29] offset:256
	v_add_u32_e32 v158, 0x40000, v153
	global_load_dwordx4 v[208:211], v158, s[28:29]
	global_load_dwordx4 v[212:215], v158, s[28:29] offset:256
	v_add_u32_e32 v159, 0x48000, v153
	global_load_dwordx4 v[216:219], v159, s[28:29]
	global_load_dwordx4 v[220:223], v159, s[28:29] offset:256
	v_add_u32_e32 v158, 0x50000, v153
	global_load_dwordx4 v[224:227], v158, s[28:29]
	global_load_dwordx4 v[228:231], v158, s[28:29] offset:256
	v_add_u32_e32 v159, 0x58000, v153
	global_load_dwordx4 v[232:235], v159, s[28:29]
	global_load_dwordx4 v[236:239], v159, s[28:29] offset:256
	s_waitcnt vmcnt(15)
	v_lshlrev_b32_e32 v128, 16, v154
	v_and_b32_e32 v129, 0xffff0000, v154
	v_lshlrev_b32_e32 v130, 16, v155
	v_and_b32_e32 v131, 0xffff0000, v155
	v_lshlrev_b32_e32 v132, 16, v156
	v_and_b32_e32 v133, 0xffff0000, v156
	v_lshlrev_b32_e32 v134, 16, v157
	v_and_b32_e32 v135, 0xffff0000, v157
	v_pk_fma_f32 v[128:129], v[124:125], s[4:5], v[128:129]
	v_pk_fma_f32 v[130:131], v[126:127], s[4:5], v[130:131]
	v_pk_fma_f32 v[132:133], v[120:121], s[4:5], v[132:133]
	v_pk_fma_f32 v[134:135], v[122:123], s[4:5], v[134:135]
	v_cvt_pk_bf16_f32 v154, v128, v129
	v_cvt_pk_bf16_f32 v155, v130, v131
	v_cvt_pk_bf16_f32 v156, v132, v133
	v_cvt_pk_bf16_f32 v157, v134, v135
	global_store_dwordx4 v153, v[154:157], s[28:29]
	v_pk_mul_f32 v[124:125], v[128:129], v[128:129]
	v_pk_fma_f32 v[124:125], v[130:131], v[130:131], v[124:125]
	v_pk_fma_f32 v[124:125], v[132:133], v[132:133], v[124:125]
	v_pk_fma_f32 v[124:125], v[134:135], v[134:135], v[124:125]
	s_waitcnt vmcnt(15)
	v_lshlrev_b32_e32 v128, 16, v180
	v_and_b32_e32 v129, 0xffff0000, v180
	v_lshlrev_b32_e32 v130, 16, v181
	v_and_b32_e32 v131, 0xffff0000, v181
	v_lshlrev_b32_e32 v132, 16, v182
	v_and_b32_e32 v133, 0xffff0000, v182
	v_lshlrev_b32_e32 v134, 16, v183
	v_and_b32_e32 v135, 0xffff0000, v183
	v_pk_fma_f32 v[128:129], v[116:117], s[4:5], v[128:129]
	v_pk_fma_f32 v[130:131], v[118:119], s[4:5], v[130:131]
	v_pk_fma_f32 v[132:133], v[112:113], s[4:5], v[132:133]
	v_pk_fma_f32 v[134:135], v[114:115], s[4:5], v[134:135]
	v_cvt_pk_bf16_f32 v180, v128, v129
	v_cvt_pk_bf16_f32 v181, v130, v131
	v_cvt_pk_bf16_f32 v182, v132, v133
	v_cvt_pk_bf16_f32 v183, v134, v135
	global_store_dwordx4 v153, v[180:183], s[28:29] offset:256
	v_pk_fma_f32 v[124:125], v[128:129], v[128:129], v[124:125]
	v_pk_fma_f32 v[124:125], v[130:131], v[130:131], v[124:125]
	v_pk_fma_f32 v[124:125], v[132:133], v[132:133], v[124:125]
	v_pk_fma_f32 v[124:125], v[134:135], v[134:135], v[124:125]
	v_add_f32_e32 v124, v124, v125
	v_add_u32_e32 v158, 0x8000, v153
	s_waitcnt vmcnt(15)
	v_lshlrev_b32_e32 v128, 16, v184
	v_and_b32_e32 v129, 0xffff0000, v184
	v_lshlrev_b32_e32 v130, 16, v185
	v_and_b32_e32 v131, 0xffff0000, v185
	v_lshlrev_b32_e32 v132, 16, v186
	v_and_b32_e32 v133, 0xffff0000, v186
	v_lshlrev_b32_e32 v134, 16, v187
	v_and_b32_e32 v135, 0xffff0000, v187
	v_pk_fma_f32 v[128:129], v[108:109], s[4:5], v[128:129]
	v_pk_fma_f32 v[130:131], v[110:111], s[4:5], v[130:131]
	v_pk_fma_f32 v[132:133], v[104:105], s[4:5], v[132:133]
	v_pk_fma_f32 v[134:135], v[106:107], s[4:5], v[134:135]
	v_cvt_pk_bf16_f32 v184, v128, v129
	v_cvt_pk_bf16_f32 v185, v130, v131
	v_cvt_pk_bf16_f32 v186, v132, v133
	v_cvt_pk_bf16_f32 v187, v134, v135
	global_store_dwordx4 v158, v[184:187], s[28:29]
	v_pk_mul_f32 v[108:109], v[128:129], v[128:129]
	v_pk_fma_f32 v[108:109], v[130:131], v[130:131], v[108:109]
	v_pk_fma_f32 v[108:109], v[132:133], v[132:133], v[108:109]
	v_pk_fma_f32 v[108:109], v[134:135], v[134:135], v[108:109]
	s_waitcnt vmcnt(15)
	v_lshlrev_b32_e32 v128, 16, v188
	v_and_b32_e32 v129, 0xffff0000, v188
	v_lshlrev_b32_e32 v130, 16, v189
	v_and_b32_e32 v131, 0xffff0000, v189
	v_lshlrev_b32_e32 v132, 16, v190
	v_and_b32_e32 v133, 0xffff0000, v190
	v_lshlrev_b32_e32 v134, 16, v191
	v_and_b32_e32 v135, 0xffff0000, v191
	v_pk_fma_f32 v[128:129], v[100:101], s[4:5], v[128:129]
	v_pk_fma_f32 v[130:131], v[102:103], s[4:5], v[130:131]
	v_pk_fma_f32 v[132:133], v[96:97], s[4:5], v[132:133]
	v_pk_fma_f32 v[134:135], v[98:99], s[4:5], v[134:135]
	v_cvt_pk_bf16_f32 v188, v128, v129
	v_cvt_pk_bf16_f32 v189, v130, v131
	v_cvt_pk_bf16_f32 v190, v132, v133
	v_cvt_pk_bf16_f32 v191, v134, v135
	global_store_dwordx4 v158, v[188:191], s[28:29] offset:256
	v_pk_fma_f32 v[108:109], v[128:129], v[128:129], v[108:109]
	v_pk_fma_f32 v[108:109], v[130:131], v[130:131], v[108:109]
	v_pk_fma_f32 v[108:109], v[132:133], v[132:133], v[108:109]
	v_pk_fma_f32 v[108:109], v[134:135], v[134:135], v[108:109]
	v_add_f32_e32 v108, v108, v109
	v_add_u32_e32 v158, 0x10000, v153
	s_waitcnt vmcnt(15)
	v_lshlrev_b32_e32 v128, 16, v192
	v_and_b32_e32 v129, 0xffff0000, v192
	v_lshlrev_b32_e32 v130, 16, v193
	v_and_b32_e32 v131, 0xffff0000, v193
	v_lshlrev_b32_e32 v132, 16, v194
	v_and_b32_e32 v133, 0xffff0000, v194
	v_lshlrev_b32_e32 v134, 16, v195
	v_and_b32_e32 v135, 0xffff0000, v195
	v_pk_fma_f32 v[128:129], v[92:93], s[4:5], v[128:129]
	v_pk_fma_f32 v[130:131], v[94:95], s[4:5], v[130:131]
	v_pk_fma_f32 v[132:133], v[88:89], s[4:5], v[132:133]
	v_pk_fma_f32 v[134:135], v[90:91], s[4:5], v[134:135]
	v_cvt_pk_bf16_f32 v192, v128, v129
	v_cvt_pk_bf16_f32 v193, v130, v131
	v_cvt_pk_bf16_f32 v194, v132, v133
	v_cvt_pk_bf16_f32 v195, v134, v135
	global_store_dwordx4 v158, v[192:195], s[28:29]
	v_pk_mul_f32 v[92:93], v[128:129], v[128:129]
	v_pk_fma_f32 v[92:93], v[130:131], v[130:131], v[92:93]
	v_pk_fma_f32 v[92:93], v[132:133], v[132:133], v[92:93]
	v_pk_fma_f32 v[92:93], v[134:135], v[134:135], v[92:93]
	s_waitcnt vmcnt(15)
	v_lshlrev_b32_e32 v128, 16, v196
	v_and_b32_e32 v129, 0xffff0000, v196
	v_lshlrev_b32_e32 v130, 16, v197
	v_and_b32_e32 v131, 0xffff0000, v197
	v_lshlrev_b32_e32 v132, 16, v198
	v_and_b32_e32 v133, 0xffff0000, v198
	v_lshlrev_b32_e32 v134, 16, v199
	v_and_b32_e32 v135, 0xffff0000, v199
	v_pk_fma_f32 v[128:129], v[84:85], s[4:5], v[128:129]
	v_pk_fma_f32 v[130:131], v[86:87], s[4:5], v[130:131]
	v_pk_fma_f32 v[132:133], v[80:81], s[4:5], v[132:133]
	v_pk_fma_f32 v[134:135], v[82:83], s[4:5], v[134:135]
	v_cvt_pk_bf16_f32 v196, v128, v129
	v_cvt_pk_bf16_f32 v197, v130, v131
	v_cvt_pk_bf16_f32 v198, v132, v133
	v_cvt_pk_bf16_f32 v199, v134, v135
	global_store_dwordx4 v158, v[196:199], s[28:29] offset:256
	v_pk_fma_f32 v[92:93], v[128:129], v[128:129], v[92:93]
	v_pk_fma_f32 v[92:93], v[130:131], v[130:131], v[92:93]
	v_pk_fma_f32 v[92:93], v[132:133], v[132:133], v[92:93]
	v_pk_fma_f32 v[92:93], v[134:135], v[134:135], v[92:93]
	v_add_f32_e32 v92, v92, v93
	v_add_u32_e32 v158, 0x18000, v153
	s_waitcnt vmcnt(15)
	v_lshlrev_b32_e32 v128, 16, v200
	v_and_b32_e32 v129, 0xffff0000, v200
	v_lshlrev_b32_e32 v130, 16, v201
	v_and_b32_e32 v131, 0xffff0000, v201
	v_lshlrev_b32_e32 v132, 16, v202
	v_and_b32_e32 v133, 0xffff0000, v202
	v_lshlrev_b32_e32 v134, 16, v203
	v_and_b32_e32 v135, 0xffff0000, v203
	v_pk_fma_f32 v[128:129], v[76:77], s[4:5], v[128:129]
	v_pk_fma_f32 v[130:131], v[78:79], s[4:5], v[130:131]
	v_pk_fma_f32 v[132:133], v[72:73], s[4:5], v[132:133]
	v_pk_fma_f32 v[134:135], v[74:75], s[4:5], v[134:135]
	v_cvt_pk_bf16_f32 v200, v128, v129
	v_cvt_pk_bf16_f32 v201, v130, v131
	v_cvt_pk_bf16_f32 v202, v132, v133
	v_cvt_pk_bf16_f32 v203, v134, v135
	global_store_dwordx4 v158, v[200:203], s[28:29]
	v_pk_mul_f32 v[76:77], v[128:129], v[128:129]
	v_pk_fma_f32 v[76:77], v[130:131], v[130:131], v[76:77]
	v_pk_fma_f32 v[76:77], v[132:133], v[132:133], v[76:77]
	v_pk_fma_f32 v[76:77], v[134:135], v[134:135], v[76:77]
	s_waitcnt vmcnt(15)
	v_lshlrev_b32_e32 v128, 16, v204
	v_and_b32_e32 v129, 0xffff0000, v204
	v_lshlrev_b32_e32 v130, 16, v205
	v_and_b32_e32 v131, 0xffff0000, v205
	v_lshlrev_b32_e32 v132, 16, v206
	v_and_b32_e32 v133, 0xffff0000, v206
	v_lshlrev_b32_e32 v134, 16, v207
	v_and_b32_e32 v135, 0xffff0000, v207
	v_pk_fma_f32 v[128:129], v[68:69], s[4:5], v[128:129]
	v_pk_fma_f32 v[130:131], v[70:71], s[4:5], v[130:131]
	v_pk_fma_f32 v[132:133], v[64:65], s[4:5], v[132:133]
	v_pk_fma_f32 v[134:135], v[66:67], s[4:5], v[134:135]
	v_cvt_pk_bf16_f32 v204, v128, v129
	v_cvt_pk_bf16_f32 v205, v130, v131
	v_cvt_pk_bf16_f32 v206, v132, v133
	v_cvt_pk_bf16_f32 v207, v134, v135
	global_store_dwordx4 v158, v[204:207], s[28:29] offset:256
	v_pk_fma_f32 v[76:77], v[128:129], v[128:129], v[76:77]
	v_pk_fma_f32 v[76:77], v[130:131], v[130:131], v[76:77]
	v_pk_fma_f32 v[76:77], v[132:133], v[132:133], v[76:77]
	v_pk_fma_f32 v[76:77], v[134:135], v[134:135], v[76:77]
	v_add_f32_e32 v76, v76, v77
	v_add_u32_e32 v158, 0x40000, v153
	s_waitcnt vmcnt(15)
	v_lshlrev_b32_e32 v128, 16, v208
	v_and_b32_e32 v129, 0xffff0000, v208
	v_lshlrev_b32_e32 v130, 16, v209
	v_and_b32_e32 v131, 0xffff0000, v209
	v_lshlrev_b32_e32 v132, 16, v210
	v_and_b32_e32 v133, 0xffff0000, v210
	v_lshlrev_b32_e32 v134, 16, v211
	v_and_b32_e32 v135, 0xffff0000, v211
	v_pk_fma_f32 v[128:129], v[60:61], s[4:5], v[128:129]
	v_pk_fma_f32 v[130:131], v[62:63], s[4:5], v[130:131]
	v_pk_fma_f32 v[132:133], v[56:57], s[4:5], v[132:133]
	v_pk_fma_f32 v[134:135], v[58:59], s[4:5], v[134:135]
	v_cvt_pk_bf16_f32 v208, v128, v129
	v_cvt_pk_bf16_f32 v209, v130, v131
	v_cvt_pk_bf16_f32 v210, v132, v133
	v_cvt_pk_bf16_f32 v211, v134, v135
	global_store_dwordx4 v158, v[208:211], s[28:29]
	v_pk_mul_f32 v[60:61], v[128:129], v[128:129]
	v_pk_fma_f32 v[60:61], v[130:131], v[130:131], v[60:61]
	v_pk_fma_f32 v[60:61], v[132:133], v[132:133], v[60:61]
	v_pk_fma_f32 v[60:61], v[134:135], v[134:135], v[60:61]
	s_waitcnt vmcnt(15)
	v_lshlrev_b32_e32 v128, 16, v212
	v_and_b32_e32 v129, 0xffff0000, v212
	v_lshlrev_b32_e32 v130, 16, v213
	v_and_b32_e32 v131, 0xffff0000, v213
	v_lshlrev_b32_e32 v132, 16, v214
	v_and_b32_e32 v133, 0xffff0000, v214
	v_lshlrev_b32_e32 v134, 16, v215
	v_and_b32_e32 v135, 0xffff0000, v215
	v_pk_fma_f32 v[128:129], v[52:53], s[4:5], v[128:129]
	v_pk_fma_f32 v[130:131], v[54:55], s[4:5], v[130:131]
	v_pk_fma_f32 v[132:133], v[48:49], s[4:5], v[132:133]
	v_pk_fma_f32 v[134:135], v[50:51], s[4:5], v[134:135]
	v_cvt_pk_bf16_f32 v212, v128, v129
	v_cvt_pk_bf16_f32 v213, v130, v131
	v_cvt_pk_bf16_f32 v214, v132, v133
	v_cvt_pk_bf16_f32 v215, v134, v135
	global_store_dwordx4 v158, v[212:215], s[28:29] offset:256
	v_pk_fma_f32 v[60:61], v[128:129], v[128:129], v[60:61]
	v_pk_fma_f32 v[60:61], v[130:131], v[130:131], v[60:61]
	v_pk_fma_f32 v[60:61], v[132:133], v[132:133], v[60:61]
	v_pk_fma_f32 v[60:61], v[134:135], v[134:135], v[60:61]
	v_add_f32_e32 v60, v60, v61
	v_add_u32_e32 v158, 0x48000, v153
	s_waitcnt vmcnt(15)
	v_lshlrev_b32_e32 v128, 16, v216
	v_and_b32_e32 v129, 0xffff0000, v216
	v_lshlrev_b32_e32 v130, 16, v217
	v_and_b32_e32 v131, 0xffff0000, v217
	v_lshlrev_b32_e32 v132, 16, v218
	v_and_b32_e32 v133, 0xffff0000, v218
	v_lshlrev_b32_e32 v134, 16, v219
	v_and_b32_e32 v135, 0xffff0000, v219
	v_pk_fma_f32 v[128:129], v[44:45], s[4:5], v[128:129]
	v_pk_fma_f32 v[130:131], v[46:47], s[4:5], v[130:131]
	v_pk_fma_f32 v[132:133], v[40:41], s[4:5], v[132:133]
	v_pk_fma_f32 v[134:135], v[42:43], s[4:5], v[134:135]
	v_cvt_pk_bf16_f32 v216, v128, v129
	v_cvt_pk_bf16_f32 v217, v130, v131
	v_cvt_pk_bf16_f32 v218, v132, v133
	v_cvt_pk_bf16_f32 v219, v134, v135
	global_store_dwordx4 v158, v[216:219], s[28:29]
	v_pk_mul_f32 v[44:45], v[128:129], v[128:129]
	v_pk_fma_f32 v[44:45], v[130:131], v[130:131], v[44:45]
	v_pk_fma_f32 v[44:45], v[132:133], v[132:133], v[44:45]
	v_pk_fma_f32 v[44:45], v[134:135], v[134:135], v[44:45]
	s_waitcnt vmcnt(15)
	v_lshlrev_b32_e32 v128, 16, v220
	v_and_b32_e32 v129, 0xffff0000, v220
	v_lshlrev_b32_e32 v130, 16, v221
	v_and_b32_e32 v131, 0xffff0000, v221
	v_lshlrev_b32_e32 v132, 16, v222
	v_and_b32_e32 v133, 0xffff0000, v222
	v_lshlrev_b32_e32 v134, 16, v223
	v_and_b32_e32 v135, 0xffff0000, v223
	v_pk_fma_f32 v[128:129], v[36:37], s[4:5], v[128:129]
	v_pk_fma_f32 v[130:131], v[38:39], s[4:5], v[130:131]
	v_pk_fma_f32 v[132:133], v[32:33], s[4:5], v[132:133]
	v_pk_fma_f32 v[134:135], v[34:35], s[4:5], v[134:135]
	v_cvt_pk_bf16_f32 v220, v128, v129
	v_cvt_pk_bf16_f32 v221, v130, v131
	v_cvt_pk_bf16_f32 v222, v132, v133
	v_cvt_pk_bf16_f32 v223, v134, v135
	global_store_dwordx4 v158, v[220:223], s[28:29] offset:256
	v_pk_fma_f32 v[44:45], v[128:129], v[128:129], v[44:45]
	v_pk_fma_f32 v[44:45], v[130:131], v[130:131], v[44:45]
	v_pk_fma_f32 v[44:45], v[132:133], v[132:133], v[44:45]
	v_pk_fma_f32 v[44:45], v[134:135], v[134:135], v[44:45]
	v_add_f32_e32 v44, v44, v45
	v_add_u32_e32 v158, 0x50000, v153
	s_waitcnt vmcnt(15)
	v_lshlrev_b32_e32 v128, 16, v224
	v_and_b32_e32 v129, 0xffff0000, v224
	v_lshlrev_b32_e32 v130, 16, v225
	v_and_b32_e32 v131, 0xffff0000, v225
	v_lshlrev_b32_e32 v132, 16, v226
	v_and_b32_e32 v133, 0xffff0000, v226
	v_lshlrev_b32_e32 v134, 16, v227
	v_and_b32_e32 v135, 0xffff0000, v227
	v_pk_fma_f32 v[128:129], v[28:29], s[4:5], v[128:129]
	v_pk_fma_f32 v[130:131], v[30:31], s[4:5], v[130:131]
	v_pk_fma_f32 v[132:133], v[24:25], s[4:5], v[132:133]
	v_pk_fma_f32 v[134:135], v[26:27], s[4:5], v[134:135]
	v_cvt_pk_bf16_f32 v224, v128, v129
	v_cvt_pk_bf16_f32 v225, v130, v131
	v_cvt_pk_bf16_f32 v226, v132, v133
	v_cvt_pk_bf16_f32 v227, v134, v135
	global_store_dwordx4 v158, v[224:227], s[28:29]
	v_pk_mul_f32 v[28:29], v[128:129], v[128:129]
	v_pk_fma_f32 v[28:29], v[130:131], v[130:131], v[28:29]
	v_pk_fma_f32 v[28:29], v[132:133], v[132:133], v[28:29]
	v_pk_fma_f32 v[28:29], v[134:135], v[134:135], v[28:29]
	s_waitcnt vmcnt(15)
	v_lshlrev_b32_e32 v128, 16, v228
	v_and_b32_e32 v129, 0xffff0000, v228
	v_lshlrev_b32_e32 v130, 16, v229
	v_and_b32_e32 v131, 0xffff0000, v229
	v_lshlrev_b32_e32 v132, 16, v230
	v_and_b32_e32 v133, 0xffff0000, v230
	v_lshlrev_b32_e32 v134, 16, v231
	v_and_b32_e32 v135, 0xffff0000, v231
	v_pk_fma_f32 v[128:129], v[20:21], s[4:5], v[128:129]
	v_pk_fma_f32 v[130:131], v[22:23], s[4:5], v[130:131]
	v_pk_fma_f32 v[132:133], v[16:17], s[4:5], v[132:133]
	v_pk_fma_f32 v[134:135], v[18:19], s[4:5], v[134:135]
	v_cvt_pk_bf16_f32 v228, v128, v129
	v_cvt_pk_bf16_f32 v229, v130, v131
	v_cvt_pk_bf16_f32 v230, v132, v133
	v_cvt_pk_bf16_f32 v231, v134, v135
	global_store_dwordx4 v158, v[228:231], s[28:29] offset:256
	v_pk_fma_f32 v[28:29], v[128:129], v[128:129], v[28:29]
	v_pk_fma_f32 v[28:29], v[130:131], v[130:131], v[28:29]
	v_pk_fma_f32 v[28:29], v[132:133], v[132:133], v[28:29]
	v_pk_fma_f32 v[28:29], v[134:135], v[134:135], v[28:29]
	v_add_f32_e32 v28, v28, v29
	v_add_u32_e32 v158, 0x58000, v153
	s_waitcnt vmcnt(15)
	v_lshlrev_b32_e32 v128, 16, v232
	v_and_b32_e32 v129, 0xffff0000, v232
	v_lshlrev_b32_e32 v130, 16, v233
	v_and_b32_e32 v131, 0xffff0000, v233
	v_lshlrev_b32_e32 v132, 16, v234
	v_and_b32_e32 v133, 0xffff0000, v234
	v_lshlrev_b32_e32 v134, 16, v235
	v_and_b32_e32 v135, 0xffff0000, v235
	v_pk_fma_f32 v[128:129], v[12:13], s[4:5], v[128:129]
	v_pk_fma_f32 v[130:131], v[14:15], s[4:5], v[130:131]
	v_pk_fma_f32 v[132:133], v[8:9], s[4:5], v[132:133]
	v_pk_fma_f32 v[134:135], v[10:11], s[4:5], v[134:135]
	v_cvt_pk_bf16_f32 v232, v128, v129
	v_cvt_pk_bf16_f32 v233, v130, v131
	v_cvt_pk_bf16_f32 v234, v132, v133
	v_cvt_pk_bf16_f32 v235, v134, v135
	global_store_dwordx4 v158, v[232:235], s[28:29]
	v_pk_mul_f32 v[12:13], v[128:129], v[128:129]
	v_pk_fma_f32 v[12:13], v[130:131], v[130:131], v[12:13]
	v_pk_fma_f32 v[12:13], v[132:133], v[132:133], v[12:13]
	v_pk_fma_f32 v[12:13], v[134:135], v[134:135], v[12:13]
	s_waitcnt vmcnt(15)
	v_lshlrev_b32_e32 v128, 16, v236
	v_and_b32_e32 v129, 0xffff0000, v236
	v_lshlrev_b32_e32 v130, 16, v237
	v_and_b32_e32 v131, 0xffff0000, v237
	v_lshlrev_b32_e32 v132, 16, v238
	v_and_b32_e32 v133, 0xffff0000, v238
	v_lshlrev_b32_e32 v134, 16, v239
	v_and_b32_e32 v135, 0xffff0000, v239
	v_pk_fma_f32 v[128:129], v[4:5], s[4:5], v[128:129]
	v_pk_fma_f32 v[130:131], v[6:7], s[4:5], v[130:131]
	v_pk_fma_f32 v[132:133], v[0:1], s[4:5], v[132:133]
	v_pk_fma_f32 v[134:135], v[2:3], s[4:5], v[134:135]
	v_cvt_pk_bf16_f32 v236, v128, v129
	v_cvt_pk_bf16_f32 v237, v130, v131
	v_cvt_pk_bf16_f32 v238, v132, v133
	v_cvt_pk_bf16_f32 v239, v134, v135
	global_store_dwordx4 v158, v[236:239], s[28:29] offset:256
	v_pk_fma_f32 v[12:13], v[128:129], v[128:129], v[12:13]
	v_pk_fma_f32 v[12:13], v[130:131], v[130:131], v[12:13]
	v_pk_fma_f32 v[12:13], v[132:133], v[132:133], v[12:13]
	v_pk_fma_f32 v[12:13], v[134:135], v[134:135], v[12:13]
	v_add_f32_e32 v12, v12, v13
	v_xor_b32_e32 v158, 16, v164
	v_xor_b32_e32 v159, 32, v164
	v_lshlrev_b32_e32 v158, 2, v158
	v_lshlrev_b32_e32 v159, 2, v159
	ds_bpermute_b32 v125, v158, v124
	ds_bpermute_b32 v109, v158, v108
	ds_bpermute_b32 v93, v158, v92
	ds_bpermute_b32 v77, v158, v76
	ds_bpermute_b32 v61, v158, v60
	ds_bpermute_b32 v45, v158, v44
	ds_bpermute_b32 v29, v158, v28
	ds_bpermute_b32 v13, v158, v12
	s_waitcnt lgkmcnt(0)
	v_add_f32_e32 v124, v124, v125
	v_add_f32_e32 v108, v108, v109
	v_add_f32_e32 v92, v92, v93
	v_add_f32_e32 v76, v76, v77
	v_add_f32_e32 v60, v60, v61
	v_add_f32_e32 v44, v44, v45
	v_add_f32_e32 v28, v28, v29
	v_add_f32_e32 v12, v12, v13
	ds_bpermute_b32 v125, v159, v124
	ds_bpermute_b32 v109, v159, v108
	ds_bpermute_b32 v93, v159, v92
	ds_bpermute_b32 v77, v159, v76
	ds_bpermute_b32 v61, v159, v60
	ds_bpermute_b32 v45, v159, v44
	ds_bpermute_b32 v29, v159, v28
	ds_bpermute_b32 v13, v159, v12
	s_waitcnt lgkmcnt(0)
	v_add_f32_e32 v124, v124, v125
	v_add_f32_e32 v108, v108, v109
	v_add_f32_e32 v92, v92, v93
	v_add_f32_e32 v76, v76, v77
	v_add_f32_e32 v60, v60, v61
	v_add_f32_e32 v44, v44, v45
	v_add_f32_e32 v28, v28, v29
	v_add_f32_e32 v12, v12, v13
	v_readlane_b32 vcc_lo, v179, 16
	v_readlane_b32 vcc_hi, v179, 17
	v_readlane_b32 s7, v240, 62
	s_and_saveexec_b64 s[96:97], vcc
	s_cbranch_execz .Lresid_ssq_done
	s_lshl_b32 s82, s47, 2
	s_add_i32 s82, s82, s7
	s_lshl_b32 s82, s82, 2
	v_lshl_add_u32 v153, v152, 6, s82
	v_add_u32_e32 v158, 0x2000, v153
	global_store_dword v153, v124, s[16:17]
	global_store_dword v153, v108, s[16:17] offset:1024
	global_store_dword v153, v92, s[16:17] offset:2048
	global_store_dword v153, v76, s[16:17] offset:3072
	global_store_dword v158, v60, s[16:17]
	global_store_dword v158, v44, s[16:17] offset:1024
	global_store_dword v158, v28, s[16:17] offset:2048
	global_store_dword v158, v12, s[16:17] offset:3072
.Lresid_ssq_done:
	s_or_b64 exec, exec, s[96:97]
	s_mov_b64 s[94:95], 0

.LBB0_542:
	v_and_b32_e32 v2, 15, v117
	s_lshl_b32 s24, s34, 7
	v_lshlrev_b32_e32 v0, 3, v2
	s_lshl_b32 s30, s39, 8
	s_and_b32 s38, s24, 0x180
	s_mov_b64 s[24:25], -1
	s_andn2_b64 vcc, exec, s[28:29]
	v_and_b32_e32 v3, 24, v0
	v_or_b32_e32 v11, 1, v0
	v_bitop3_b32 v4, v0, 25, 1 bitop3:0xc8
	v_or_b32_e32 v12, 2, v0
	v_bitop3_b32 v5, v0, 26, 2 bitop3:0xc8
	v_or_b32_e32 v13, 3, v0
	v_bitop3_b32 v6, v0, 27, 3 bitop3:0xc8
	v_or_b32_e32 v14, 4, v0
	s_waitcnt lgkmcnt(0)
	v_bitop3_b32 v7, v0, 28, 4 bitop3:0xc8
	v_or_b32_e32 v15, 5, v0
	v_bitop3_b32 v8, v0, 29, 5 bitop3:0xc8
	v_or_b32_e32 v16, 6, v0
	v_bitop3_b32 v9, v0, 30, 6 bitop3:0xc8
	v_or_b32_e32 v17, 7, v0
	v_bitop3_b32 v10, v0, 31, 7 bitop3:0xc8
	s_cbranch_vccnz .LBB0_546
	v_lshrrev_b32_e32 v170, 4, v117
	v_and_b32_e32 v171, 15, v117
	v_add_u32_e32 v172, s30, v170
	v_lshlrev_b32_e32 v172, 11, v172
	s_lshl_b32 s24, s38, 2
	v_lshl_add_u32 v172, v171, 5, v172
	v_add_u32_e32 v172, s24, v172
	v_and_b32_e32 v173, 15, v170
	v_xor_b32_e32 v173, v173, v171
	v_lshlrev_b32_e32 v173, 4, v173
	v_lshl_add_u32 v173, v170, 8, v173
	v_and_b32_e32 v174, 3, v170
	v_lshlrev_b32_e32 v174, 2, v174
	v_xor_b32_e32 v174, v174, v171
	v_lshlrev_b32_e32 v174, 4, v174
	v_lshl_add_u32 v174, v170, 8, v174
	v_add_u32_e32 v174, 0x10000, v174
	global_load_dwordx4 v[176:179], v172, s[2:3]
	global_load_dwordx4 v[180:183], v172, s[2:3] offset:16
	global_load_dwordx4 v[184:187], v172, s[4:5]
	global_load_dwordx4 v[188:191], v172, s[4:5] offset:16
	v_add_u32_e32 v172, 0x10000, v172
	global_load_dwordx4 v[192:195], v172, s[2:3]
	global_load_dwordx4 v[196:199], v172, s[2:3] offset:16
	global_load_dwordx4 v[200:203], v172, s[4:5]
	global_load_dwordx4 v[204:207], v172, s[4:5] offset:16
	v_add_u32_e32 v172, 0x10000, v172
	global_load_dwordx4 v[208:211], v172, s[2:3]
	global_load_dwordx4 v[212:215], v172, s[2:3] offset:16
	global_load_dwordx4 v[216:219], v172, s[4:5]
	global_load_dwordx4 v[220:223], v172, s[4:5] offset:16
	v_add_u32_e32 v172, 0x10000, v172
	global_load_dwordx4 v[224:227], v172, s[2:3]
	global_load_dwordx4 v[228:231], v172, s[2:3] offset:16
	global_load_dwordx4 v[232:235], v172, s[4:5]
	global_load_dwordx4 v[236:239], v172, s[4:5] offset:16
	v_add_u32_e32 v172, 0x10000, v172
	s_waitcnt vmcnt(12)
	v_cvt_pk_bf16_f32 v176, v176, v177
	v_cvt_pk_bf16_f32 v177, v178, v179
	v_cvt_pk_bf16_f32 v178, v180, v181
	v_cvt_pk_bf16_f32 v179, v182, v183
	v_cvt_pk_bf16_f32 v184, v184, v185
	v_cvt_pk_bf16_f32 v185, v186, v187
	v_cvt_pk_bf16_f32 v186, v188, v189
	v_cvt_pk_bf16_f32 v187, v190, v191
	ds_write_b128 v173, v[176:179]
	ds_write_b128 v174, v[184:187]
	global_load_dwordx4 v[176:179], v172, s[2:3]
	global_load_dwordx4 v[180:183], v172, s[2:3] offset:16
	global_load_dwordx4 v[184:187], v172, s[4:5]
	global_load_dwordx4 v[188:191], v172, s[4:5] offset:16
	v_add_u32_e32 v172, 0x10000, v172
	s_waitcnt vmcnt(12)
	v_cvt_pk_bf16_f32 v192, v192, v193
	v_cvt_pk_bf16_f32 v193, v194, v195
	v_cvt_pk_bf16_f32 v194, v196, v197
	v_cvt_pk_bf16_f32 v195, v198, v199
	v_cvt_pk_bf16_f32 v200, v200, v201
	v_cvt_pk_bf16_f32 v201, v202, v203
	v_cvt_pk_bf16_f32 v202, v204, v205
	v_cvt_pk_bf16_f32 v203, v206, v207
	ds_write_b128 v173, v[192:195] offset:8192
	ds_write_b128 v174, v[200:203] offset:8192
	global_load_dwordx4 v[192:195], v172, s[2:3]
	global_load_dwordx4 v[196:199], v172, s[2:3] offset:16
	global_load_dwordx4 v[200:203], v172, s[4:5]
	global_load_dwordx4 v[204:207], v172, s[4:5] offset:16
	v_add_u32_e32 v172, 0x10000, v172
	s_waitcnt vmcnt(12)
	v_cvt_pk_bf16_f32 v208, v208, v209
	v_cvt_pk_bf16_f32 v209, v210, v211
	v_cvt_pk_bf16_f32 v210, v212, v213
	v_cvt_pk_bf16_f32 v211, v214, v215
	v_cvt_pk_bf16_f32 v216, v216, v217
	v_cvt_pk_bf16_f32 v217, v218, v219
	v_cvt_pk_bf16_f32 v218, v220, v221
	v_cvt_pk_bf16_f32 v219, v222, v223
	ds_write_b128 v173, v[208:211] offset:16384
	ds_write_b128 v174, v[216:219] offset:16384
	global_load_dwordx4 v[208:211], v172, s[2:3]
	global_load_dwordx4 v[212:215], v172, s[2:3] offset:16
	global_load_dwordx4 v[216:219], v172, s[4:5]
	global_load_dwordx4 v[220:223], v172, s[4:5] offset:16
	v_add_u32_e32 v172, 0x10000, v172
	s_waitcnt vmcnt(12)
	v_cvt_pk_bf16_f32 v224, v224, v225
	v_cvt_pk_bf16_f32 v225, v226, v227
	v_cvt_pk_bf16_f32 v226, v228, v229
	v_cvt_pk_bf16_f32 v227, v230, v231
	v_cvt_pk_bf16_f32 v232, v232, v233
	v_cvt_pk_bf16_f32 v233, v234, v235
	v_cvt_pk_bf16_f32 v234, v236, v237
	v_cvt_pk_bf16_f32 v235, v238, v239
	ds_write_b128 v173, v[224:227] offset:24576
	ds_write_b128 v174, v[232:235] offset:24576
	global_load_dwordx4 v[224:227], v172, s[2:3]
	global_load_dwordx4 v[228:231], v172, s[2:3] offset:16
	global_load_dwordx4 v[232:235], v172, s[4:5]
	global_load_dwordx4 v[236:239], v172, s[4:5] offset:16
	s_waitcnt vmcnt(12)
	v_cvt_pk_bf16_f32 v176, v176, v177
	v_cvt_pk_bf16_f32 v177, v178, v179
	v_cvt_pk_bf16_f32 v178, v180, v181
	v_cvt_pk_bf16_f32 v179, v182, v183
	v_cvt_pk_bf16_f32 v184, v184, v185
	v_cvt_pk_bf16_f32 v185, v186, v187
	v_cvt_pk_bf16_f32 v186, v188, v189
	v_cvt_pk_bf16_f32 v187, v190, v191
	ds_write_b128 v173, v[176:179] offset:32768
	ds_write_b128 v174, v[184:187] offset:32768
	s_waitcnt vmcnt(8)
	v_cvt_pk_bf16_f32 v192, v192, v193
	v_cvt_pk_bf16_f32 v193, v194, v195
	v_cvt_pk_bf16_f32 v194, v196, v197
	v_cvt_pk_bf16_f32 v195, v198, v199
	v_cvt_pk_bf16_f32 v200, v200, v201
	v_cvt_pk_bf16_f32 v201, v202, v203
	v_cvt_pk_bf16_f32 v202, v204, v205
	v_cvt_pk_bf16_f32 v203, v206, v207
	ds_write_b128 v173, v[192:195] offset:40960
	ds_write_b128 v174, v[200:203] offset:40960
	s_waitcnt vmcnt(4)
	v_cvt_pk_bf16_f32 v208, v208, v209
	v_cvt_pk_bf16_f32 v209, v210, v211
	v_cvt_pk_bf16_f32 v210, v212, v213
	v_cvt_pk_bf16_f32 v211, v214, v215
	v_cvt_pk_bf16_f32 v216, v216, v217
	v_cvt_pk_bf16_f32 v217, v218, v219
	v_cvt_pk_bf16_f32 v218, v220, v221
	v_cvt_pk_bf16_f32 v219, v222, v223
	ds_write_b128 v173, v[208:211] offset:49152
	ds_write_b128 v174, v[216:219] offset:49152
	s_waitcnt vmcnt(0)
	v_cvt_pk_bf16_f32 v224, v224, v225
	v_cvt_pk_bf16_f32 v225, v226, v227
	v_cvt_pk_bf16_f32 v226, v228, v229
	v_cvt_pk_bf16_f32 v227, v230, v231
	v_cvt_pk_bf16_f32 v232, v232, v233
	v_cvt_pk_bf16_f32 v233, v234, v235
	v_cvt_pk_bf16_f32 v234, v236, v237
	v_cvt_pk_bf16_f32 v235, v238, v239
	ds_write_b128 v173, v[224:227] offset:57344
	ds_write_b128 v174, v[232:235] offset:57344
	s_mov_b64 s[24:25], 0
.LBB0_546:
	s_and_b64 vcc, exec, s[24:25]
	s_cbranch_vccz .LBB0_549
	v_lshrrev_b32_e32 v170, 4, v117
	v_and_b32_e32 v171, 15, v117
	v_add_u32_e32 v172, s30, v170
	v_lshlrev_b32_e32 v172, 11, v172
	s_lshl_b32 s24, s38, 1
	s_add_u32 s24, s41, s24
	s_addc_u32 s25, s78, 0
	v_lshl_add_u32 v172, v171, 4, v172
	v_and_b32_e32 v173, 15, v170
	v_xor_b32_e32 v173, v173, v171
	v_lshlrev_b32_e32 v173, 4, v173
	v_lshl_add_u32 v173, v170, 8, v173
	v_and_b32_e32 v174, 3, v170
	v_lshlrev_b32_e32 v174, 2, v174
	v_xor_b32_e32 v174, v174, v171
	v_lshlrev_b32_e32 v174, 4, v174
	v_lshl_add_u32 v174, v170, 8, v174
	v_add_u32_e32 v174, 0x10000, v174
	global_load_dwordx4 v[176:179], v172, s[24:25]
	global_load_dwordx4 v[180:183], v172, s[24:25] offset:1024
	v_add_u32_e32 v172, 0x10000, v172
	global_load_dwordx4 v[184:187], v172, s[24:25]
	global_load_dwordx4 v[188:191], v172, s[24:25] offset:1024
	v_add_u32_e32 v172, 0x10000, v172
	global_load_dwordx4 v[192:195], v172, s[24:25]
	global_load_dwordx4 v[196:199], v172, s[24:25] offset:1024
	v_add_u32_e32 v172, 0x10000, v172
	global_load_dwordx4 v[200:203], v172, s[24:25]
	global_load_dwordx4 v[204:207], v172, s[24:25] offset:1024
	v_add_u32_e32 v172, 0x10000, v172
	global_load_dwordx4 v[208:211], v172, s[24:25]
	global_load_dwordx4 v[212:215], v172, s[24:25] offset:1024
	v_add_u32_e32 v172, 0x10000, v172
	global_load_dwordx4 v[216:219], v172, s[24:25]
	global_load_dwordx4 v[220:223], v172, s[24:25] offset:1024
	v_add_u32_e32 v172, 0x10000, v172
	global_load_dwordx4 v[224:227], v172, s[24:25]
	global_load_dwordx4 v[228:231], v172, s[24:25] offset:1024
	v_add_u32_e32 v172, 0x10000, v172
	global_load_dwordx4 v[232:235], v172, s[24:25]
	global_load_dwordx4 v[236:239], v172, s[24:25] offset:1024
	s_waitcnt vmcnt(14)
	ds_write_b128 v173, v[176:179]
	ds_write_b128 v174, v[180:183]
	s_waitcnt vmcnt(12)
	ds_write_b128 v173, v[184:187] offset:8192
	ds_write_b128 v174, v[188:191] offset:8192
	s_waitcnt vmcnt(10)
	ds_write_b128 v173, v[192:195] offset:16384
	ds_write_b128 v174, v[196:199] offset:16384
	s_waitcnt vmcnt(8)
	ds_write_b128 v173, v[200:203] offset:24576
	ds_write_b128 v174, v[204:207] offset:24576
	s_waitcnt vmcnt(6)
	ds_write_b128 v173, v[208:211] offset:32768
	ds_write_b128 v174, v[212:215] offset:32768
	s_waitcnt vmcnt(4)
	ds_write_b128 v173, v[216:219] offset:40960
	ds_write_b128 v174, v[220:223] offset:40960
	s_waitcnt vmcnt(2)
	ds_write_b128 v173, v[224:227] offset:49152
	ds_write_b128 v174, v[228:231] offset:49152
	s_waitcnt vmcnt(0)
	ds_write_b128 v173, v[232:235] offset:57344
	ds_write_b128 v174, v[236:239] offset:57344

.LBB0_554:
	v_readlane_b32 s28, v240, 26
	v_readlane_b32 s29, v240, 27
	s_lshl_b32 s34, s38, 1
	v_mad_i64_i32 v[0:1], s[28:29], s28, v116, 0
	v_lshl_add_u64 v[0:1], v[0:1], 1, s[6:7]
	v_lshrrev_b32_e32 v3, 1, v117
	v_lshl_add_u64 v[0:1], v[0:1], 0, s[34:35]
	v_and_b32_e32 v136, 16, v3
	v_lshl_add_u64 v[0:1], v[0:1], 0, v[136:137]
	global_load_dwordx4 v[80:83], v[0:1], off
	global_load_dwordx4 v[84:87], v[0:1], off offset:32
	global_load_dwordx4 v[88:91], v[0:1], off offset:64
	global_load_dwordx4 v[92:95], v[0:1], off offset:96
	global_load_dwordx4 v[96:99], v[0:1], off offset:128
	global_load_dwordx4 v[100:103], v[0:1], off offset:160
	global_load_dwordx4 v[104:107], v[0:1], off offset:192
	global_load_dwordx4 v[108:111], v[0:1], off offset:224
	v_bfe_u32 v120, v117, 5, 1
	v_lshlrev_b32_e32 v4, 8, v119
	v_and_b32_e32 v6, 64, v164
	v_bitop3_b32 v9, v120, v2, 10 bitop3:0x36
	v_xor_b32_e32 v5, 32, v164
	v_add_u32_e32 v6, 64, v6
	v_bitop3_b32 v8, v120, v2, 8 bitop3:0x36
	v_lshl_or_b32 v0, v9, 4, v4
	v_cmp_lt_i32_e32 vcc, v5, v6
	v_bitop3_b32 v7, v120, v2, 6 bitop3:0x36
	v_add_u32_e32 v125, 0, v0
	v_lshl_or_b32 v0, v8, 4, v4
	v_lshrrev_b32_e32 v3, 5, v117
	v_cndmask_b32_e32 v5, v164, v5, vcc
	v_bitop3_b32 v6, v120, v2, 4 bitop3:0x36
	v_add_u32_e32 v126, 0, v0
	v_lshl_or_b32 v0, v7, 4, v4
	v_lshlrev_b32_e32 v121, 2, v5
	v_bitop3_b32 v3, v3, v2, 1 bitop3:0x6c
	v_bitop3_b32 v5, v120, v2, 2 bitop3:0x36
	v_bitop3_b32 v10, v120, v2, 12 bitop3:0x36
	v_bitop3_b32 v2, v120, v2, 14 bitop3:0x36
	v_add_u32_e32 v127, 0, v0
	v_lshl_or_b32 v0, v6, 4, v4
	v_lshl_or_b32 v2, v2, 4, v4
	v_add_u32_e32 v128, 0, v0
	v_lshl_or_b32 v0, v5, 4, v4
	s_add_i32 s29, 0, 0x10000
	v_add_u32_e32 v123, 0, v2
	v_lshl_or_b32 v2, v10, 4, v4
	v_add_u32_e32 v129, 0, v0
	v_lshl_or_b32 v0, v3, 4, v4
	v_mov_b32_e32 v131, 0
	s_mov_b32 s28, 0
	v_lshl_add_u32 v122, v119, 9, s29
	v_add_u32_e32 v124, 0, v2
	v_add_u32_e32 v130, 0, v0
	v_mov_b32_e32 v132, 0xff800000
	v_mov_b32_e32 v0, 0
	v_mov_b32_e32 v1, v131
	v_mov_b32_e32 v2, v131
	v_mov_b32_e32 v3, v131
	v_mov_b32_e32 v4, v131
	v_mov_b32_e32 v5, v131
	v_mov_b32_e32 v6, v131
	v_mov_b32_e32 v7, v131
	v_mov_b32_e32 v8, v131
	v_mov_b32_e32 v9, v131
	v_mov_b32_e32 v10, v131
	v_mov_b32_e32 v11, v131
	v_mov_b32_e32 v12, v131
	v_mov_b32_e32 v13, v131
	v_mov_b32_e32 v14, v131
	v_mov_b32_e32 v15, v131
	v_mov_b32_e32 v16, 0
	v_mov_b32_e32 v17, v131
	v_mov_b32_e32 v18, v131
	v_mov_b32_e32 v19, v131
	v_mov_b32_e32 v20, v131
	v_mov_b32_e32 v21, v131
	v_mov_b32_e32 v22, v131
	v_mov_b32_e32 v23, v131
	v_mov_b32_e32 v24, v131
	v_mov_b32_e32 v25, v131
	v_mov_b32_e32 v26, v131
	v_mov_b32_e32 v27, v131
	v_mov_b32_e32 v28, v131
	v_mov_b32_e32 v29, v131
	v_mov_b32_e32 v30, v131
	v_mov_b32_e32 v31, v131
	v_mov_b32_e32 v32, 0
	v_mov_b32_e32 v33, v131
	v_mov_b32_e32 v34, v131
	v_mov_b32_e32 v35, v131
	v_mov_b32_e32 v36, v131
	v_mov_b32_e32 v37, v131
	v_mov_b32_e32 v38, v131
	v_mov_b32_e32 v39, v131
	v_mov_b32_e32 v40, v131
	v_mov_b32_e32 v41, v131
	v_mov_b32_e32 v42, v131
	v_mov_b32_e32 v43, v131
	v_mov_b32_e32 v44, v131
	v_mov_b32_e32 v45, v131
	v_mov_b32_e32 v46, v131
	v_mov_b32_e32 v47, v131
	v_mov_b32_e32 v48, 0
	v_mov_b32_e32 v49, v131
	v_mov_b32_e32 v50, v131
	v_mov_b32_e32 v51, v131
	v_mov_b32_e32 v52, v131
	v_mov_b32_e32 v53, v131
	v_mov_b32_e32 v54, v131
	v_mov_b32_e32 v55, v131
	v_mov_b32_e32 v56, v131
	v_mov_b32_e32 v57, v131
	v_mov_b32_e32 v58, v131
	v_mov_b32_e32 v59, v131
	v_mov_b32_e32 v60, v131
	v_mov_b32_e32 v61, v131
	v_mov_b32_e32 v62, v131
	v_mov_b32_e32 v63, v131
	v_and_b32_e32 v170, 63, v117
	v_bfe_u32 v171, v170, 2, 2
	v_and_b32_e32 v172, 3, v170
	v_lshlrev_b32_e32 v173, 8, v171
	v_lshl_add_u32 v173, v172, 3, v173
	v_bfe_u32 v172, v170, 4, 1
	v_lshl_add_u32 v173, v172, 5, v173
	v_lshrrev_b32_e32 v172, 5, v170
	v_lshl_add_u32 v173, v172, 10, v173
	v_add_u32_e32 v173, 0x10000, v173
	v_lshl_add_u32 v174, v171, 6, v173
	v_xor_b32_e32 v170, 1, v171
	v_lshl_add_u32 v175, v170, 6, v173
	v_xor_b32_e32 v170, 2, v171
	v_lshl_add_u32 v176, v170, 6, v173
	v_xor_b32_e32 v170, 3, v171
	v_lshl_add_u32 v177, v170, 6, v173
.LBB0_555:
	v_add_u32_e32 v64, s28, v130
	ds_read_b128 v[64:67], v64
	v_add_u32_e32 v139, s28, v129
	ds_read_b128 v[140:143], v139
	v_add_u32_e32 v138, s28, v128
	v_add_u32_e32 v136, s28, v127
	v_add_u32_e32 v135, s28, v126
	v_add_u32_e32 v134, s28, v125
	v_add_u32_e32 v114, s28, v124
	v_add_u32_e32 v112, s28, v123
	s_waitcnt vmcnt(7) lgkmcnt(1)
	v_mfma_f32_32x32x16_bf16 v[64:79], v[64:67], v[80:83], 0
	v_mov_b32_e32 v118, v132
	s_addk_i32 s28, 0x2000
	s_waitcnt vmcnt(6) lgkmcnt(0)
	v_mfma_f32_32x32x16_bf16 v[64:79], v[140:143], v[84:87], v[64:79]
	ds_read_b128 v[138:141], v138
	s_cmp_lg_u32 s28, 0x10000
	s_waitcnt vmcnt(5) lgkmcnt(0)
	v_mfma_f32_32x32x16_bf16 v[64:79], v[138:141], v[88:91], v[64:79]
	ds_read_b128 v[138:141], v136
	s_waitcnt vmcnt(4) lgkmcnt(0)
	v_mfma_f32_32x32x16_bf16 v[64:79], v[138:141], v[92:95], v[64:79]
	ds_read_b128 v[138:141], v135
	s_waitcnt vmcnt(3) lgkmcnt(0)
	v_mfma_f32_32x32x16_bf16 v[64:79], v[138:141], v[96:99], v[64:79]
	ds_read_b128 v[138:141], v134
	s_waitcnt vmcnt(2) lgkmcnt(0)
	v_mfma_f32_32x32x16_bf16 v[64:79], v[138:141], v[100:103], v[64:79]
	ds_read_b128 v[138:141], v114
	ds_read_b128 v[142:145], v112
	s_waitcnt vmcnt(1) lgkmcnt(1)
	v_mfma_f32_32x32x16_bf16 v[64:79], v[138:141], v[104:107], v[64:79]
	ds_read_b64_tr_b16 v[138:139], v174
	ds_read_b64_tr_b16 v[140:141], v175
	ds_read_b64_tr_b16 v[148:149], v176
	ds_read_b64_tr_b16 v[150:151], v177
	ds_read_b64_tr_b16 v[112:113], v174 offset:2048
	ds_read_b64_tr_b16 v[114:115], v175 offset:2048
	s_waitcnt vmcnt(0) lgkmcnt(6)
	v_mfma_f32_32x32x16_bf16 v[64:79], v[142:145], v[108:111], v[64:79]
	s_nop 11
	v_mul_f32_e32 v132, 0x3db504f3, v64
	v_mul_f32_e32 v136, 0x3db504f3, v65
	v_mul_f32_e32 v142, 0x3db504f3, v66
	v_mul_f32_e32 v143, 0x3db504f3, v67
	v_max3_f32 v132, v132, s33, v136
	v_mul_f32_e32 v144, 0x3db504f3, v68
	v_mul_f32_e32 v145, 0x3db504f3, v69
	v_max3_f32 v132, v132, v142, v143
	v_mul_f32_e32 v146, 0x3db504f3, v70
	v_mul_f32_e32 v152, 0x3db504f3, v71
	v_max3_f32 v132, v132, v144, v145
	v_mul_f32_e32 v153, 0x3db504f3, v72
	v_mul_f32_e32 v154, 0x3db504f3, v73
	v_max3_f32 v132, v132, v146, v152
	v_mul_f32_e32 v155, 0x3db504f3, v74
	v_mul_f32_e32 v156, 0x3db504f3, v75
	v_max3_f32 v132, v132, v153, v154
	v_mul_f32_e32 v157, 0x3db504f3, v76
	v_mul_f32_e32 v158, 0x3db504f3, v77
	v_max3_f32 v132, v132, v155, v156
	v_mul_f32_e32 v159, 0x3db504f3, v78
	v_mul_f32_e32 v160, 0x3db504f3, v79
	v_max3_f32 v132, v132, v157, v158
	v_max3_f32 v132, v132, v159, v160
	ds_bpermute_b32 v136, v121, v132
	s_waitcnt lgkmcnt(5)
	v_mov_b32_e32 v142, v138
	v_mov_b32_e32 v143, v139
	s_waitcnt lgkmcnt(1)
	v_mov_b32_e32 v144, v112
	v_mov_b32_e32 v145, v113
	s_waitcnt lgkmcnt(0)
	v_max3_f32 v132, v118, v132, v136
	v_fma_f32 v136, v64, s22, -v132
	v_fma_f32 v146, v65, s22, -v132
	v_fma_f32 v152, v66, s22, -v132
	v_fma_f32 v153, v67, s22, -v132
	v_fma_f32 v154, v68, s22, -v132
	v_fma_f32 v155, v69, s22, -v132
	v_fma_f32 v156, v70, s22, -v132
	v_fma_f32 v157, v71, s22, -v132
	ds_read_b64_tr_b16 v[68:69], v176 offset:2048
	ds_read_b64_tr_b16 v[70:71], v177 offset:2048
	ds_read_b64_tr_b16 v[64:65], v174 offset:4096
	ds_read_b64_tr_b16 v[66:67], v175 offset:4096
	v_fma_f32 v166, v76, s22, -v132
	v_sub_f32_e32 v76, v118, v132
	v_mul_f32_e32 v76, 0x3fb8aa3b, v76
	v_mul_f32_e32 v118, 0x3fb8aa3b, v153
	v_fma_f32 v158, v72, s22, -v132
	v_fma_f32 v159, v73, s22, -v132
	v_fma_f32 v160, v74, s22, -v132
	v_fma_f32 v161, v75, s22, -v132
	v_mov_b32_e32 v72, v148
	v_mov_b32_e32 v73, v149
	s_waitcnt lgkmcnt(2)
	v_mov_b32_e32 v74, v68
	v_mov_b32_e32 v75, v69
	v_mov_b32_e32 v68, v150
	v_exp_f32_e32 v150, v118
	v_exp_f32_e32 v118, v76
	v_fma_f32 v167, v77, s22, -v132
	v_fma_f32 v168, v78, s22, -v132
	v_fma_f32 v169, v79, s22, -v132
	v_mov_b32_e32 v112, v140
	v_mov_b32_e32 v113, v141
	v_mul_f32_e32 v77, 0x3fb8aa3b, v136
	v_mul_f32_e32 v78, 0x3fb8aa3b, v146
	v_mul_f32_e32 v79, 0x3fb8aa3b, v152
	v_mul_f32_e32 v134, 0x3fb8aa3b, v154
	v_mul_f32_e32 v136, 0x3fb8aa3b, v155
	v_mul_f32_e32 v138, 0x3fb8aa3b, v156
	v_mul_f32_e32 v139, 0x3fb8aa3b, v157
	v_pk_mul_f32 v[46:47], v[46:47], v[118:119] op_sel_hi:[1,0]
	v_pk_mul_f32 v[44:45], v[44:45], v[118:119] op_sel_hi:[1,0]
	v_pk_mul_f32 v[42:43], v[42:43], v[118:119] op_sel_hi:[1,0]
	v_pk_mul_f32 v[40:41], v[40:41], v[118:119] op_sel_hi:[1,0]
	v_pk_mul_f32 v[38:39], v[38:39], v[118:119] op_sel_hi:[1,0]
	v_pk_mul_f32 v[36:37], v[36:37], v[118:119] op_sel_hi:[1,0]
	v_pk_mul_f32 v[34:35], v[34:35], v[118:119] op_sel_hi:[1,0]
	v_pk_mul_f32 v[32:33], v[32:33], v[118:119] op_sel_hi:[1,0]
	v_pk_mul_f32 v[14:15], v[14:15], v[118:119] op_sel_hi:[1,0]
	v_pk_mul_f32 v[12:13], v[12:13], v[118:119] op_sel_hi:[1,0]
	v_pk_mul_f32 v[10:11], v[10:11], v[118:119] op_sel_hi:[1,0]
	v_pk_mul_f32 v[8:9], v[8:9], v[118:119] op_sel_hi:[1,0]
	v_pk_mul_f32 v[6:7], v[6:7], v[118:119] op_sel_hi:[1,0]
	v_pk_mul_f32 v[4:5], v[4:5], v[118:119] op_sel_hi:[1,0]
	v_pk_mul_f32 v[2:3], v[2:3], v[118:119] op_sel_hi:[1,0]
	v_pk_mul_f32 v[0:1], v[0:1], v[118:119] op_sel_hi:[1,0]
	v_mov_b32_e32 v69, v151
	v_exp_f32_e32 v146, v77
	v_exp_f32_e32 v148, v78
	v_exp_f32_e32 v149, v79
	v_exp_f32_e32 v134, v134
	v_exp_f32_e32 v136, v136
	v_exp_f32_e32 v151, v138
	v_exp_f32_e32 v152, v139
	v_cvt_pk_bf16_f32 v76, v146, v148
	v_cvt_pk_bf16_f32 v77, v149, v150
	v_cvt_pk_bf16_f32 v78, v134, v136
	v_cvt_pk_bf16_f32 v79, v151, v152
	v_pk_mul_f32 v[30:31], v[30:31], v[118:119] op_sel_hi:[1,0]
	v_mfma_f32_32x32x16_bf16 v[32:47], v[142:145], v[76:79], v[32:47]
	ds_read_b64_tr_b16 v[138:139], v174 offset:6144
	ds_read_b64_tr_b16 v[140:141], v175 offset:6144
	ds_read_b64_tr_b16 v[142:143], v176 offset:4096
	ds_read_b64_tr_b16 v[144:145], v177 offset:4096
	v_mul_f32_e64 v28, v28, v118
	v_mul_f32_e64 v29, v29, v118
	v_mul_f32_e64 v26, v26, v118
	v_mul_f32_e64 v27, v27, v118
	v_pk_mul_f32 v[24:25], v[24:25], v[118:119] op_sel_hi:[1,0]
	v_pk_mul_f32 v[22:23], v[22:23], v[118:119] op_sel_hi:[1,0]
	v_pk_mul_f32 v[20:21], v[20:21], v[118:119] op_sel_hi:[1,0]
	v_pk_mul_f32 v[18:19], v[18:19], v[118:119] op_sel_hi:[1,0]
	v_mfma_f32_32x32x16_bf16 v[0:15], v[72:75], v[76:79], v[0:15]
	ds_read_b64_tr_b16 v[72:73], v176 offset:6144
	ds_read_b64_tr_b16 v[74:75], v177 offset:6144
	v_mul_f32_e64 v16, v16, v118
	v_mul_f32_e64 v17, v17, v118
	v_mul_f32_e64 v62, v62, v118
	v_mul_f32_e64 v63, v63, v118
	v_pk_mul_f32 v[60:61], v[60:61], v[118:119] op_sel_hi:[1,0]
	v_pk_mul_f32 v[58:59], v[58:59], v[118:119] op_sel_hi:[1,0]
	v_pk_mul_f32 v[56:57], v[56:57], v[118:119] op_sel_hi:[1,0]
	v_pk_mul_f32 v[54:55], v[54:55], v[118:119] op_sel_hi:[1,0]
	v_mfma_f32_32x32x16_bf16 v[16:31], v[112:115], v[76:79], v[16:31]
	s_waitcnt lgkmcnt(6)
	v_mov_b32_e32 v112, v64
	v_mov_b32_e32 v113, v65
	s_waitcnt lgkmcnt(4)
	v_mov_b32_e32 v114, v138
	v_mov_b32_e32 v115, v139
	v_mul_f32_e32 v64, 0x3fb8aa3b, v158
	v_mul_f32_e32 v65, 0x3fb8aa3b, v159
	v_mul_f32_e32 v138, 0x3fb8aa3b, v161
	v_mul_f32_e32 v139, 0x3fb8aa3b, v166
	v_exp_f32_e32 v156, v64
	v_exp_f32_e32 v157, v65
	v_exp_f32_e32 v158, v138
	v_exp_f32_e32 v159, v139
	v_mov_b32_e32 v138, v66
	v_mov_b32_e32 v139, v67
	s_waitcnt lgkmcnt(2)
	v_mov_b32_e32 v64, v142
	v_mov_b32_e32 v65, v143
	s_waitcnt lgkmcnt(0)
	v_mov_b32_e32 v66, v72
	v_mov_b32_e32 v67, v73
	v_pk_mul_f32 v[52:53], v[52:53], v[118:119] op_sel_hi:[1,0]
	v_pk_mul_f32 v[50:51], v[50:51], v[118:119] op_sel_hi:[1,0]
	v_pk_mul_f32 v[48:49], v[48:49], v[118:119] op_sel_hi:[1,0]
	v_fmac_f32_e32 v146, v131, v118
	v_mul_f32_e32 v135, 0x3fb8aa3b, v160
	v_mfma_f32_32x32x16_bf16 v[48:63], v[68:71], v[76:79], v[48:63]
	v_mul_f32_e32 v153, 0x3fb8aa3b, v167
	v_mul_f32_e32 v154, 0x3fb8aa3b, v168
	v_mul_f32_e32 v155, 0x3fb8aa3b, v169
	v_add_f32_e32 v79, v148, v146
	v_exp_f32_e32 v135, v135
	v_exp_f32_e32 v76, v153
	v_exp_f32_e32 v77, v154
	v_exp_f32_e32 v78, v155
	v_cvt_pk_bf16_f32 v68, v156, v157
	v_cvt_pk_bf16_f32 v69, v135, v158
	v_cvt_pk_bf16_f32 v70, v159, v76
	v_cvt_pk_bf16_f32 v71, v77, v78
	v_mov_b32_e32 v72, v144
	v_mfma_f32_32x32x16_bf16 v[0:15], v[64:67], v[68:71], v[0:15]
	v_add_f32_e32 v64, v149, v79
	v_mov_b32_e32 v73, v145
	v_add_f32_e32 v64, v150, v64
	v_add_f32_e32 v64, v134, v64
	v_add_f32_e32 v64, v136, v64
	v_add_f32_e32 v64, v151, v64
	v_add_f32_e32 v64, v152, v64
	v_mfma_f32_32x32x16_bf16 v[32:47], v[112:115], v[68:71], v[32:47]
	v_add_f32_e32 v64, v156, v64
	v_add_f32_e32 v64, v157, v64
	v_add_f32_e32 v64, v135, v64
	v_add_f32_e32 v64, v158, v64
	v_add_f32_e32 v64, v159, v64
	v_add_f32_e32 v64, v76, v64
	v_add_f32_e32 v64, v77, v64
	v_mfma_f32_32x32x16_bf16 v[16:31], v[138:141], v[68:71], v[16:31]
	v_add_f32_e32 v131, v78, v64
	v_mfma_f32_32x32x16_bf16 v[48:63], v[72:75], v[68:71], v[48:63]
	v_add_u32_e32 v174, 0x2000, v174
	v_add_u32_e32 v175, 0x2000, v175
	v_add_u32_e32 v176, 0x2000, v176
	v_add_u32_e32 v177, 0x2000, v177
	s_cbranch_scc1 .LBB0_555
	ds_bpermute_b32 v64, v121, v131
	v_cmp_gt_u32_e32 vcc, 8, v119
	s_or_b64 s[0:1], s[0:1], vcc
	s_and_b64 exec, exec, s[0:1]
	s_cbranch_execz .LBB0_454
	v_sub_f32_e32 v65, 0xff800000, v132
	v_mul_f32_e32 v65, 0x3fb8aa3b, v65
	v_exp_f32_e32 v65, v65
	s_waitcnt lgkmcnt(0)
	v_add_f32_e32 v64, v131, v64
	s_lshl_b32 s34, s38, 1
	v_add_f32_e32 v64, v65, v64
	v_div_scale_f32 v65, s[0:1], v64, v64, 1.0
	v_rcp_f32_e32 v66, v65
	v_div_scale_f32 v67, vcc, 1.0, v64, 1.0
	v_readlane_b32 s0, v243, 54
	v_fma_f32 v68, -v65, v66, 1.0
	v_fmac_f32_e32 v66, v68, v66
	v_mul_f32_e32 v68, v67, v66
	v_fma_f32 v69, -v65, v68, v67
	v_fmac_f32_e32 v68, v69, v66
	v_fma_f32 v65, -v65, v68, v67
	v_div_fmas_f32 v65, v65, v66, v68
	v_div_fixup_f32 v64, v65, v64, 1.0
	v_readlane_b32 s1, v243, 55
	v_mul_f32_e32 v67, v1, v64
	v_mul_f32_e32 v68, v0, v64
	v_mov_b64_e32 v[0:1], s[0:1]
	s_movk_i32 s0, 0xc00
	v_mul_f32_e32 v66, v2, v64
	v_mul_f32_e32 v2, v33, v64
	v_mad_i64_i32 v[0:1], s[0:1], v116, s0, v[0:1]
	v_lshrrev_b32_e32 v33, 2, v117
	v_mul_f32_e32 v65, v3, v64
	v_mul_f32_e32 v3, v35, v64
	v_lshl_add_u64 v[0:1], v[0:1], 0, s[34:35]
	v_and_b32_e32 v136, 8, v33
	v_mul_f32_e32 v34, v34, v64
	v_mul_f32_e32 v32, v32, v64
	v_lshl_add_u64 v[0:1], v[0:1], 0, v[136:137]
	v_cvt_pk_bf16_f32 v2, v32, v2
	v_cvt_pk_bf16_f32 v3, v34, v3
	v_mul_f32_e32 v39, v39, v64
	v_mul_f32_e32 v38, v38, v64
	v_mul_f32_e32 v37, v37, v64
	v_mul_f32_e32 v36, v36, v64
	global_store_dwordx2 v[0:1], v[2:3], off offset:2048
	v_cvt_pk_bf16_f32 v2, v36, v37
	v_cvt_pk_bf16_f32 v3, v38, v39
	v_mul_f32_e32 v43, v43, v64
	v_mul_f32_e32 v42, v42, v64
	v_mul_f32_e32 v41, v41, v64
	v_mul_f32_e32 v40, v40, v64
	global_store_dwordx2 v[0:1], v[2:3], off offset:2064
	v_cvt_pk_bf16_f32 v2, v40, v41
	v_cvt_pk_bf16_f32 v3, v42, v43
	v_mul_f32_e32 v47, v47, v64
	v_mul_f32_e32 v46, v46, v64
	v_mul_f32_e32 v45, v45, v64
	v_mul_f32_e32 v44, v44, v64
	global_store_dwordx2 v[0:1], v[2:3], off offset:2080
	v_cvt_pk_bf16_f32 v2, v44, v45
	v_cvt_pk_bf16_f32 v3, v46, v47
	v_mul_f32_e32 v19, v19, v64
	v_mul_f32_e32 v18, v18, v64
	v_mul_f32_e32 v17, v17, v64
	v_mul_f32_e32 v16, v16, v64
	global_store_dwordx2 v[0:1], v[2:3], off offset:2096
	v_cvt_pk_bf16_f32 v2, v16, v17
	v_cvt_pk_bf16_f32 v3, v18, v19
	v_mul_f32_e32 v23, v23, v64
	v_mul_f32_e32 v22, v22, v64
	v_mul_f32_e32 v21, v21, v64
	v_mul_f32_e32 v20, v20, v64
	global_store_dwordx2 v[0:1], v[2:3], off offset:2112
	v_cvt_pk_bf16_f32 v2, v20, v21
	v_cvt_pk_bf16_f32 v3, v22, v23
	v_mul_f32_e32 v27, v27, v64
	v_mul_f32_e32 v26, v26, v64
	v_mul_f32_e32 v25, v25, v64
	v_mul_f32_e32 v24, v24, v64
	global_store_dwordx2 v[0:1], v[2:3], off offset:2128
	v_cvt_pk_bf16_f32 v2, v24, v25
	v_cvt_pk_bf16_f32 v3, v26, v27
	v_mul_f32_e32 v31, v31, v64
	v_mul_f32_e32 v30, v30, v64
	v_mul_f32_e32 v29, v29, v64
	v_mul_f32_e32 v28, v28, v64
	global_store_dwordx2 v[0:1], v[2:3], off offset:2144
	v_cvt_pk_bf16_f32 v2, v28, v29
	v_cvt_pk_bf16_f32 v3, v30, v31
	global_store_dwordx2 v[0:1], v[2:3], off offset:2160
	v_cvt_pk_bf16_f32 v2, v68, v67
	v_cvt_pk_bf16_f32 v3, v66, v65
	v_mul_f32_e32 v7, v7, v64
	v_mul_f32_e32 v6, v6, v64
	v_mul_f32_e32 v5, v5, v64
	v_mul_f32_e32 v4, v4, v64
	global_store_dwordx2 v[0:1], v[2:3], off offset:2176
	v_cvt_pk_bf16_f32 v2, v4, v5
	v_cvt_pk_bf16_f32 v3, v6, v7
	v_mul_f32_e32 v11, v11, v64
	v_mul_f32_e32 v10, v10, v64
	v_mul_f32_e32 v9, v9, v64
	v_mul_f32_e32 v8, v8, v64
	global_store_dwordx2 v[0:1], v[2:3], off offset:2192
	v_cvt_pk_bf16_f32 v2, v8, v9
	v_cvt_pk_bf16_f32 v3, v10, v11
	v_mul_f32_e32 v15, v15, v64
	v_mul_f32_e32 v14, v14, v64
	v_mul_f32_e32 v13, v13, v64
	v_mul_f32_e32 v12, v12, v64
	global_store_dwordx2 v[0:1], v[2:3], off offset:2208
	v_cvt_pk_bf16_f32 v2, v12, v13
	v_cvt_pk_bf16_f32 v3, v14, v15
	v_mul_f32_e32 v51, v51, v64
	v_mul_f32_e32 v50, v50, v64
	v_mul_f32_e32 v49, v49, v64
	v_mul_f32_e32 v48, v48, v64
	global_store_dwordx2 v[0:1], v[2:3], off offset:2224
	v_cvt_pk_bf16_f32 v2, v48, v49
	v_cvt_pk_bf16_f32 v3, v50, v51
	v_mul_f32_e32 v55, v55, v64
	v_mul_f32_e32 v54, v54, v64
	v_mul_f32_e32 v53, v53, v64
	v_mul_f32_e32 v52, v52, v64
	global_store_dwordx2 v[0:1], v[2:3], off offset:2240
	v_cvt_pk_bf16_f32 v2, v52, v53
	v_cvt_pk_bf16_f32 v3, v54, v55
	v_mul_f32_e32 v59, v59, v64
	v_mul_f32_e32 v58, v58, v64
	v_mul_f32_e32 v57, v57, v64
	v_mul_f32_e32 v56, v56, v64
	global_store_dwordx2 v[0:1], v[2:3], off offset:2256
	v_cvt_pk_bf16_f32 v2, v56, v57
	v_cvt_pk_bf16_f32 v3, v58, v59
	v_mul_f32_e32 v63, v63, v64
	v_mul_f32_e32 v62, v62, v64
	v_mul_f32_e32 v61, v61, v64
	v_mul_f32_e32 v60, v60, v64
	global_store_dwordx2 v[0:1], v[2:3], off offset:2272
	v_cvt_pk_bf16_f32 v2, v60, v61
	v_cvt_pk_bf16_f32 v3, v62, v63
	global_store_dwordx2 v[0:1], v[2:3], off offset:2288
	s_branch .LBB0_454
